# speedup vs baseline: 1.0026x; 1.0026x over previous
; __device__ __forceinline__ int ltid() { int t = threadIdx.x; asm volatile("" : "+v"(t)); return t; }
; __device__ __forceinline__ bool gemm_sched(int it, int nNt, int& mt, int& nt) {
;   const int nslots = gridDim.x >> 3;
;   const int x = blockIdx.x & 7, slot = blockIdx.x >> 3;
;   if (slot >= nslots) return false;
;   const int lt = slot + it * nslots;
;   if (lt >= 16 * nNt) return false;
;   const int grp = lt / (8 * nNt), rem = lt % (8 * nNt);
;   nt = rem >> 3;
;   mt = x * 16 + grp * 8 + (rem & 7);
;   return true;
; }
; __device__ __forceinline__ void phase_inproj(const Params& p, char* smem) {
;   char* ws = p.ws;
;   const u16* h = (const u16*)(ws + OFF_RH);
;   const u16* wt = (const u16*)(ws + OFF_WINT);
;   const int lane = ltid() & 63, wid = ltid() >> 6, wr = wid >> 1, wc = wid & 1;
;   const int fr = lane & 15, fq = lane >> 4;
;   for (int it = 0;; ++it) {
;     int mt, nt;
;     if (!gemm_sched(it, 89, mt, nt)) break;
.LBB0_118:
	s_or_b64 exec, exec, s[0:1]
	s_cmpk_lt_u32 s2, 0x100
	s_cbranch_scc1 .Lstag118
	s_sleep 16
.Lstag118:
	s_add_u32 s64, s54, 0x400000
	s_addc_u32 s65, s55, 0
	s_lshr_b32 s3, s33, 3
	s_lshr_b32 s62, s2, 3
	s_cmp_lt_u32 s62, s3
	s_cselect_b64 s[4:5], -1, 0
	s_lshl_b32 s0, s2, 4
	s_and_b32 s38, s0, 0x70
	s_add_u32 s0, s54, 0x38c00000
	s_addc_u32 s1, s55, 0
	s_add_u32 s67, s54, 0x3cc00000
	v_writelane_b32 v253, s0, 33
	s_addc_u32 s68, s55, 0
	v_mov_b32_e32 v0, v216
	v_writelane_b32 v253, s1, 34
	s_add_u32 s0, s54, 0x35d000
	s_addc_u32 s1, s55, 0
	s_add_u32 s69, s54, 0x37d000
	s_addc_u32 s70, s55, 0
	s_add_u32 s8, s54, 0x4880000
	s_barrier
	v_mov_b32_e32 v1, v216
	s_addc_u32 s9, s55, 0
	v_and_b32_e32 v229, 15, v0
	v_and_b32_e32 v2, 64, v1
	v_lshrrev_b32_e32 v0, 2, v0
	s_add_u32 s22, s54, 0x24c00000
	s_addc_u32 s23, s55, 0
	v_and_or_b32 v218, v0, 12, v2
	s_add_u32 s34, s54, 0xcc00000
	v_mov_b32_e32 v221, 0
	v_lshlrev_b32_e32 v220, 2, v218
	v_cndmask_b32_e64 v0, 0, 1, s[4:5]
	s_movk_i32 s66, 0x70
	v_and_b32_e32 v230, 0xffffff80, v1
	s_addc_u32 s35, s55, 0
	v_cmp_eq_u32_e64 s[6:7], 0, v2
	v_writelane_b32 v253, s8, 35
	v_or_b32_e32 v231, 16, v218
	v_or_b32_e32 v232, 32, v218
	v_lshl_add_u64 v[222:223], s[8:9], 0, v[220:221]
	v_or_b32_e32 v233, 48, v218
	v_cmp_ne_u32_e64 s[92:93], 1, v0
	s_mov_b32 s71, 0x60000
	s_mov_b32 s72, 0x40000
	s_mov_b32 s73, 0x20000
	s_mov_b32 s74, 0x10000
	s_mov_b32 s75, 0x30000
	s_mov_b32 s76, 0x70000
	s_mov_b32 s77, 0x28c00000
	s_movk_i32 s78, 0xffc8
	s_mov_b32 s79, 0x1cc00000
	s_movk_i32 s80, 0xffe0
	s_movk_i32 s81, 0x1800
	v_mov_b32_e32 v234, 0x2c8
	s_mov_b32 s82, 0
	v_writelane_b32 v253, s9, 36
	s_branch .LBB0_121

; __device__ __forceinline__ int ltid() { int t = threadIdx.x; asm volatile("" : "+v"(t)); return t; }
; __device__ __forceinline__ void phase_merge(const Params& p, char* smem) {
;   char* ws = p.ws;
;   u16* mg = (u16*)(ws + OFF_SBQ);
;   const int lane = ltid() & 63, wid = ltid() >> 6, wr = wid >> 1, wc = wid & 1;
;   const int fr = lane & 15, fq = lane >> 4;
;   for (int it = 0;; ++it) {
;     int mt, nt;
;     if (!gemm_sched(it, 16, mt, nt)) break;
; #pragma unroll 1
;     for (int pass = 0; pass < 2; ++pass) {
;       const u16* A = (const u16*)(ws + (pass ? OFF_DNQKV : OFF_RH + 64 * MiB));
.LBB0_943:
	s_or_b64 exec, exec, s[0:1]
	v_mov_b32_e32 v0, v216
	v_mov_b32_e32 v1, v216
	s_and_b64 vcc, exec, s[92:93]
	s_barrier
	s_cbranch_vccnz .LBB0_1017
	s_cmpk_lt_u32 s2, 0x100
	s_cbranch_scc1 .Lstag944
	s_sleep 16
.Lstag944:
	s_cmpk_gt_u32 s2, 0x7ff
	s_cbranch_scc1 .LBB0_1017
	v_lshrrev_b32_e32 v2, 2, v0
	v_and_b32_e32 v2, 12, v2
	v_and_or_b32 v192, v1, 64, v2
	v_and_b32_e32 v2, 0xffffff80, v1
	v_ashrrev_i32_e32 v1, 31, v2
	v_and_or_b32 v0, v0, 15, v2
	s_lshr_b32 s14, s2, 3
	v_lshlrev_b64 v[176:177], 11, v[0:1]
	s_mov_b32 s15, 0x8c00000
	s_mov_b32 s16, 0x3080000
	s_movk_i32 s17, 0x70
	v_mov_b32_e32 v179, 0
	s_mov_b32 s18, 0x30000
	s_mov_b32 s19, 0x20000
	s_mov_b32 s20, 0x10000
	s_mov_b32 s21, 0x70000
	s_mov_b32 s24, 0x60000
	s_mov_b32 s25, 0x50000
	s_mov_b32 s26, 0x40000
	s_mov_b32 s27, 0x28c00000
	s_mov_b32 s44, s62
	s_branch .LBB0_947

; __device__ __forceinline__ int ltid() { int t = threadIdx.x; asm volatile("" : "+v"(t)); return t; }
; #define ZERO_ACC(acc) _Pragma("unroll") for (int m_ = 0; m_ < 8; ++m_) _Pragma("unroll") for (int n_ = 0; n_ < 4; ++n_) acc[m_][n_] = (f32x4){0.f, 0.f, 0.f, 0.f};
; __device__ __forceinline__ void phase_outproj(const Params& p, char* smem) {
;   char* ws = p.ws;
;   const u16* mg = (const u16*)(ws + OFF_SBQ);
;   const u16* wo = (const u16*)(ws + OFF_WOT);
;   const float* mod = (const float*)(ws + OFF_MOD);
;   const int lane = ltid() & 63, wid = ltid() >> 6, wr = wid >> 1, wc = wid & 1;
;   const int fr = lane & 15, fq = lane >> 4;
;   for (int it = 0;; ++it) {
;     int mt, nt;
;     if (!gemm_sched(it, 16, mt, nt)) break;
;     f32x4 acc[8][4];
;     ZERO_ACC(acc);
;     gemm_tile_256<false>(mg + (size_t)mt * 256 * D, D, wo + (size_t)nt * 128 * D, D, D, smem, acc);
;     const int b = (mt * 256) >> 14;
.Lstag1028:
	s_cmpk_gt_u32 s2, 0x7ff
	s_cbranch_scc1 .LBB0_1035
	s_lshr_b32 s0, s38, 6
	s_mul_i32 s0, s0, 0xc000
	s_add_u32 s0, s54, s0
	s_addc_u32 s5, s55, 0
	v_lshrrev_b32_e32 v2, 2, v0
	s_add_u32 s4, s0, 0x5000
	v_and_b32_e32 v2, 12, v2
	s_addc_u32 s5, s5, 0
	v_and_b32_e32 v3, 0xffffff80, v1
	v_and_or_b32 v2, v1, 64, v2
	s_add_u32 s7, s54, 0x3880000
	v_ashrrev_i32_e32 v1, 31, v3
	v_and_or_b32 v0, v0, 15, v3
	s_mov_b32 s1, 0
	s_addc_u32 s10, s55, 0
	s_lshr_b32 s11, s2, 3
	v_lshlrev_b64 v[176:177], 11, v[0:1]
	s_movk_i32 s12, 0x70
	v_mov_b32_e32 v179, 0
	s_mov_b32 s13, 0x60000
	s_mov_b32 s14, 0x40000
	s_mov_b32 s15, 0x20000
	s_mov_b32 s16, 0xe0000
	s_mov_b32 s17, 0xc0000
	s_mov_b32 s18, 0xa0000
	s_mov_b32 s19, 0x80000
	v_lshlrev_b32_e32 v192, 2, v2
	s_mov_b32 s6, 0x3f9837f0
	s_mov_b32 s20, s62
	s_branch .LBB0_1031

; __device__ __forceinline__ int ltid() { int t = threadIdx.x; asm volatile("" : "+v"(t)); return t; }
; __device__ __forceinline__ void phase_peerq(const Params& p, char* smem) {
;   char* ws = p.ws;
;   const u16* h2 = (const u16*)(ws + OFF_RH);
;   const u16* wq = (const u16*)(ws + OFF_WQT);
;   float* qo = (float*)(ws + OFF_DNQKV);
;   const int lane = ltid() & 63, wid = ltid() >> 6, wr = wid >> 1, wc = wid & 1;
;   const int fr = lane & 15, fq = lane >> 4;
;   for (int it = 0;; ++it) {
;     int mt, nt;
;     if (!gemm_sched(it, 16, mt, nt)) break;
.Lstag1068:
	s_cmpk_gt_u32 s2, 0x7ff
	s_cbranch_scc1 .LBB0_1075
	v_lshrrev_b32_e32 v2, 2, v0
	v_and_b32_e32 v2, 12, v2
	v_and_b32_e32 v3, 0xffffff80, v1
	v_and_or_b32 v2, v1, 64, v2
	v_ashrrev_i32_e32 v1, 31, v3
	v_and_or_b32 v0, v0, 15, v3
	s_add_u32 s20, s54, 0x4080000
	v_lshlrev_b64 v[0:1], 13, v[0:1]
	s_addc_u32 s21, s55, 0
	s_lshr_b32 s24, s2, 3
	v_lshl_add_u64 v[176:177], s[34:35], 0, v[0:1]
	s_mov_b32 s1, 0
	s_movk_i32 s25, 0x70
	v_mov_b32_e32 v179, 0
	s_mov_b32 s26, 0x60000
	s_mov_b32 s27, 0x40000
	s_mov_b32 s36, 0x20000
	s_mov_b32 s37, 0xe0000
	s_mov_b32 s44, 0xc0000
	s_mov_b32 s45, 0xa0000
	s_mov_b32 s46, 0x80000
	v_lshlrev_b32_e32 v192, 2, v2
	s_mov_b64 s[4:5], 0x20000
	s_mov_b64 s[6:7], 0x40000
	s_mov_b64 s[8:9], 0x60000
	s_mov_b64 s[10:11], 0x80000
	s_mov_b64 s[12:13], 0xa0000
	s_mov_b64 s[14:15], 0xc0000
	s_mov_b64 s[16:17], 0xe0000
	s_branch .LBB0_1071
